# RG-LRU xc tile in LDS: 16-byte chunks XOR-swizzled for rows 4..11 mod 16, gate-MFMA fragment ds_read_b128 bank-conflict-free; on top of v88
# speedup vs baseline: 1.0131x; 1.0035x over previous
; __device__ __forceinline__ void phase_lru(const Params& p, LAS unsigned char* lds) {
;     const int tid = threadIdx.x, lane = tid & 63, wave = __builtin_amdgcn_readfirstlane(tid >> 6), g = lane >> 4, lc = lane & 15;
;     const bf16_t* XL = (const bf16_t*)(p.ws + WS_XL); bf16_t* GY = (bf16_t*)(p.ws + WS_GY); bf16_t* HF = (bf16_t*)(p.ws + WS_F);
;     const bf16_t* WG = (const bf16_t*)(p.ws + WS_WG);
;     for (int item = blockIdx.x; item < 256; item += gridDim.x) {
;         int gb, n;
;         if (item < 128) { gb = 16 + (item >> 3); n = item & 7; } else { gb = (item - 128) >> 3; n = item & 7; }
;         const int S = gb < 16 ? SP : SS; const int row0 = gb < 16 ? gb * SP : TP + (gb - 16) * SS;
;         const int nch = S >> 6;
;         const int tr = tid >> 4, cgp = (tid & 15) * 8, c0 = 128 * n + cgp;
;         float cw[4][8], cb[8];
; #pragma unroll
;         for (int j = 0; j < 4; ++j) { const f32x4 a = *(const f32x4*)(p.in[16] + j * D + c0), b = *(const f32x4*)(p.in[16] + j * D + c0 + 4);
;             cw[j][0] = a.x; cw[j][1] = a.y; cw[j][2] = a.z; cw[j][3] = a.w; cw[j][4] = b.x; cw[j][5] = b.y; cw[j][6] = b.z; cw[j][7] = b.w; }
;         { const f32x4 a = *(const f32x4*)(p.in[17] + c0), b = *(const f32x4*)(p.in[17] + c0 + 4);
;             cb[0] = a.x; cb[1] = a.y; cb[2] = a.z; cb[3] = a.w; cb[4] = b.x; cb[5] = b.y; cb[6] = b.z; cb[7] = b.w; }
;         const int ch = 128 * n + 16 * wave + lc;
;     ...
;                     *(LAS u32x4*)(lds + tl * XC_PITCH + cgp * 2) = o;
;                 }
;                 __syncthreads();
;                 if (ci + 1 < nch) LRU_PREFETCH(ci + 1);
;                 float hfv[4][4], gyv[4][4];
;                 if (d == 1) {
;                     const bf16_t* const hfi = HF + (size_t)(row0 + t0 + 4 * g) * D + ch; const bf16_t* const gyi = GY + (size_t)(row0 + t0 + 4 * g) * D + ch;
; #pragma unroll
;                     for (int mt = 0; mt < 4; ++mt)
; #pragma unroll
;                         for (int j = 0; j < 4; ++j) { hfv[mt][j] = bf2f(hfi[(16 * mt + j) * D]); gyv[mt][j] = bf2f(gyi[(16 * mt + j) * D]); }
;                 }
;                 f32x4 aa[4], ai[4];
; #pragma unroll
;                 for (int mt = 0; mt < 4; ++mt) { aa[mt] = (f32x4){0.f, 0.f, 0.f, 0.f}; ai[mt] = (f32x4){0.f, 0.f, 0.f, 0.f}; }
; #pragma unroll
;                 for (int ks = 0; ks < 4; ++ks)
; #pragma unroll
.LBB0_551:
	s_add_u32 s24, s92, 0x22000000
	s_addc_u32 s25, s93, 0
	s_add_u32 s26, s92, 0x2e000000
	s_addc_u32 s27, s93, 0
	s_cmp_lt_i32 s94, 7
	s_cselect_b64 s[28:29], -1, 0
	s_and_b64 s[0:1], s[28:29], s[0:1]
	s_andn2_b64 vcc, exec, s[0:1]
	s_cbranch_vccnz .LBB0_609
	s_cmpk_gt_i32 s2, 0xff
	v_readfirstlane_b32 s0, v128
	s_cbranch_scc1 .LBB0_600
	v_lshlrev_b32_e32 v0, 3, v128
	s_lshr_b32 s0, s0, 2
	v_and_b32_e32 v1, 15, v128
	v_and_b32_e32 v185, 0x78, v0
	s_and_b32 s0, s0, 0x3ffffff0
	v_mov_b32_e32 v0, 0
	v_or_b32_e32 v116, s0, v1
	v_mov_b32_e32 v117, v0
	v_lshlrev_b64 v[2:3], 8, v[116:117]
	v_lshl_add_u64 v[2:3], s[92:93], 0, v[2:3]
	v_and_b32_e32 v4, 48, v128
	v_mov_b32_e32 v5, v0
	v_and_b32_e32 v6, 63, v128
	v_lshl_add_u64 v[2:3], v[2:3], 0, v[4:5]
	s_mov_b64 s[0:1], 0x3080000
	v_bfe_u32 v7, v128, 4, 2
	v_lshrrev_b32_e32 v184, 4, v128
	v_lshl_add_u64 v[118:119], v[2:3], 0, s[0:1]
	v_lshlrev_b32_e32 v2, 2, v6
	v_xor_b32_e32 v117, 64, v2
	v_xor_b32_e32 v186, 0x80, v2
	v_bfe_u32 v188, v6, 4, 1
	v_cmp_lt_u32_e64 s[0:1], 31, v6
	v_lshl_add_u32 v2, v185, 1, 0
	v_add_u32_e32 v3, 0, v4
	v_lshl_add_u32 v4, v116, 1, 0
	v_mul_u32_u24_e32 v5, 0x110, v184
	v_mul_u32_u24_e32 v1, 0x110, v1
	v_mul_u32_u24_e32 v6, 0x440, v7
	v_bitop3_b32 v187, v184, 1, v184 bitop3:0xc
	s_mov_b32 s11, 0
	v_lshlrev_b32_e32 v189, 2, v7
	s_mov_b64 s[12:13], 0x1000
	s_movk_i32 s3, 0x1000
	s_waitcnt lgkmcnt(0)
	s_mov_b64 s[40:41], 0x2000
	s_movk_i32 s30, 0x2000
	s_mov_b64 s[44:45], 0x3000
	s_movk_i32 s31, 0x3000
	s_movk_i32 s34, 0x800
	s_mov_b32 s35, 0x8000
	s_mov_b32 s56, 0xbfb8aa3b
	s_mov_b32 s57, 0x42ce8ed0
	s_mov_b32 s58, 0xc2b17218
	s_mov_b32 s59, 0x7f800000
	s_mov_b32 s60, 0x3f2aaaab
	v_mov_b32_e32 v190, 0x3ecc95a3
	s_mov_b32 s61, 0x3f317218
	s_mov_b32 s62, 0x33800000
	v_add_u32_e32 v8, 4, v184
	v_and_b32_e32 v8, 8, v8
	v_lshlrev_b32_e32 v8, 1, v8
	v_xor_b32_e32 v8, v2, v8
	v_add_u32_e32 v191, v8, v5
	s_movk_i32 s63, 0xffe0
	s_movk_i32 s64, 0xffdf
	s_movk_i32 s65, 0xffde
	s_movk_i32 s66, 0xffdd
	s_mov_b32 s67, 0x9000
	s_mov_b32 s72, 0x10000
	s_mov_b32 s73, 0x11000
	s_mov_b32 s74, 0x18000
	s_mov_b32 s75, 0x19000
	v_and_b32_e32 v8, 15, v128
	v_add_u32_e32 v8, 4, v8
	v_and_b32_e32 v8, 8, v8
	v_lshlrev_b32_e32 v8, 1, v8
	v_xor_b32_e32 v8, v3, v8
	v_add_u32_e32 v192, v8, v1
	v_add_u32_e32 v8, 1, v7
	v_and_b32_e32 v8, 2, v8
	v_lshlrev_b32_e32 v8, 3, v8
	v_xor_b32_e32 v8, v4, v8
	v_add_u32_e32 v193, v8, v6
	v_mov_b32_e32 v194, 0x7f800000
	s_mov_b32 s76, s2
	s_branch .LBB0_555
